# down-GEMM residual epilogue software-pipelined in quarters (loads of the next 2 rows in flight while the current 2 rows are exchanged/added/stored)
# speedup vs baseline: 1.0061x; 1.0061x over previous
; #define EPI_FOR(u) \
;     _Pragma("unroll") for (int ai = 0; ai < 2; ++ai) _Pragma("unroll") for (int m = 0; m < 4; ++m) _Pragma("unroll") for (int bj = 0; bj < 2; ++bj)
; #define EPI_COL(u) (EPI_CB(u) + 8 * fq)
;     DI void operator()(const Acc& acc, const Unit& u, int wr, int wc, int fr, int fq) const {
;         EPI_FOR(u) {
;             const int row = EPI_ROW(u), col = EPI_COL(u);
;             const float* rp = res + (size_t)row * 1024 + col; float* op = out + (size_t)row * 1024 + col;
;             const f32x4 r0 = *(const f32x4*)rp, r1 = *(const f32x4*)(rp + 4);
;             *(f32x4*)op = r0 + acc[ai][bj][m][0]; *(f32x4*)(op + 4) = r1 + acc[ai][bj][m][1];
;         }
.LBB0_1407:
	s_lshl_b32 s2, s40, 8
	s_add_i32 s2, s2, s47
	v_readlane_b32 s62, v254, 43
	v_add_u32_e32 v240, s2, v142
	s_lshl_b32 s2, s52, 8
	s_or_b32 s2, s2, s48
	v_lshl_add_u32 v241, v143, 3, s2
	s_mov_b64 s[6:7], -1
	s_andn2_b64 vcc, exec, s[10:11]
	v_readlane_b32 s63, v254, 44
	v_lshlrev_b32_e32 v186, 12, v240
	v_lshl_add_u32 v186, v241, 2, v186
	v_and_b32_e32 v242, 8, v233
	v_mul_u32_u24_e32 v243, 0xffe, v242
	v_sub_u32_e32 v186, v186, v243
	v_add_u32_e32 v187, 0x0, v186
	v_add_u32_e32 v230, 0x8000, v186
	global_load_dwordx4 v[138:141], v187, s[16:17]
	global_load_dwordx4 v[146:149], v230, s[16:17]
	global_load_dwordx4 v[150:153], v187, s[16:17] offset:512
	global_load_dwordx4 v[154:157], v230, s[16:17] offset:512
	v_add_u32_e32 v187, 0x10000, v186
	v_add_u32_e32 v230, 0x18000, v186
	global_load_dwordx4 v[158:161], v187, s[16:17]
	global_load_dwordx4 v[162:165], v230, s[16:17]
	global_load_dwordx4 v[166:169], v187, s[16:17] offset:512
	global_load_dwordx4 v[170:173], v230, s[16:17] offset:512
	v_add_u32_e32 v187, 0x20000, v186
	v_add_u32_e32 v230, 0x28000, v186
	global_load_dwordx4 v[174:177], v187, s[16:17]
	global_load_dwordx4 v[178:181], v230, s[16:17]
	global_load_dwordx4 v[182:185], v187, s[16:17] offset:512
	global_load_dwordx4 v[210:213], v230, s[16:17] offset:512
	v_add_u32_e32 v187, 0x30000, v186
	v_add_u32_e32 v230, 0x38000, v186
	global_load_dwordx4 v[214:217], v187, s[16:17]
	global_load_dwordx4 v[218:221], v230, s[16:17]
	global_load_dwordx4 v[222:225], v187, s[16:17] offset:512
	global_load_dwordx4 v[226:229], v230, s[16:17] offset:512
	s_waitcnt vmcnt(8)
	v_mov_b32_e32 v244, v138
	v_mov_b32_e32 v245, v139
	v_mov_b32_e32 v246, v140
	v_mov_b32_e32 v247, v141
	v_mov_b32_dpp v138, v146 row_ror:8 row_mask:0xf bank_mask:0xc
	v_mov_b32_dpp v139, v147 row_ror:8 row_mask:0xf bank_mask:0xc
	v_mov_b32_dpp v140, v148 row_ror:8 row_mask:0xf bank_mask:0xc
	v_mov_b32_dpp v141, v149 row_ror:8 row_mask:0xf bank_mask:0xc
	v_mov_b32_dpp v146, v244 row_ror:8 row_mask:0xf bank_mask:0x3
	v_mov_b32_dpp v147, v245 row_ror:8 row_mask:0xf bank_mask:0x3
	v_mov_b32_dpp v148, v246 row_ror:8 row_mask:0xf bank_mask:0x3
	v_mov_b32_dpp v149, v247 row_ror:8 row_mask:0xf bank_mask:0x3
	v_pk_add_f32 v[124:125], v[124:125], v[138:139]
	v_pk_add_f32 v[126:127], v[126:127], v[140:141]
	v_pk_add_f32 v[120:121], v[120:121], v[146:147]
	v_pk_add_f32 v[122:123], v[122:123], v[148:149]
	v_mov_b32_e32 v244, v120
	v_mov_b32_e32 v245, v121
	v_mov_b32_e32 v246, v122
	v_mov_b32_e32 v247, v123
	v_mov_b32_dpp v120, v124 row_ror:8 row_mask:0xf bank_mask:0x3
	v_mov_b32_dpp v121, v125 row_ror:8 row_mask:0xf bank_mask:0x3
	v_mov_b32_dpp v122, v126 row_ror:8 row_mask:0xf bank_mask:0x3
	v_mov_b32_dpp v123, v127 row_ror:8 row_mask:0xf bank_mask:0x3
	v_mov_b32_dpp v124, v244 row_ror:8 row_mask:0xf bank_mask:0xc
	v_mov_b32_dpp v125, v245 row_ror:8 row_mask:0xf bank_mask:0xc
	v_mov_b32_dpp v126, v246 row_ror:8 row_mask:0xf bank_mask:0xc
	v_mov_b32_dpp v127, v247 row_ror:8 row_mask:0xf bank_mask:0xc
	v_add_u32_e32 v187, 0x0, v186
	v_add_u32_e32 v230, 0x8000, v186
	global_store_dwordx4 v187, v[124:127], s[16:17]
	global_store_dwordx4 v230, v[120:123], s[16:17]
	v_mov_b32_e32 v244, v150
	v_mov_b32_e32 v245, v151
	v_mov_b32_e32 v246, v152
	v_mov_b32_e32 v247, v153
	v_mov_b32_dpp v150, v154 row_ror:8 row_mask:0xf bank_mask:0xc
	v_mov_b32_dpp v151, v155 row_ror:8 row_mask:0xf bank_mask:0xc
	v_mov_b32_dpp v152, v156 row_ror:8 row_mask:0xf bank_mask:0xc
	v_mov_b32_dpp v153, v157 row_ror:8 row_mask:0xf bank_mask:0xc
	v_mov_b32_dpp v154, v244 row_ror:8 row_mask:0xf bank_mask:0x3
	v_mov_b32_dpp v155, v245 row_ror:8 row_mask:0xf bank_mask:0x3
	v_mov_b32_dpp v156, v246 row_ror:8 row_mask:0xf bank_mask:0x3
	v_mov_b32_dpp v157, v247 row_ror:8 row_mask:0xf bank_mask:0x3
	v_pk_add_f32 v[116:117], v[116:117], v[150:151]
	v_pk_add_f32 v[118:119], v[118:119], v[152:153]
	v_pk_add_f32 v[112:113], v[112:113], v[154:155]
	v_pk_add_f32 v[114:115], v[114:115], v[156:157]
	v_mov_b32_e32 v244, v112
	v_mov_b32_e32 v245, v113
	v_mov_b32_e32 v246, v114
	v_mov_b32_e32 v247, v115
	v_mov_b32_dpp v112, v116 row_ror:8 row_mask:0xf bank_mask:0x3
	v_mov_b32_dpp v113, v117 row_ror:8 row_mask:0xf bank_mask:0x3
	v_mov_b32_dpp v114, v118 row_ror:8 row_mask:0xf bank_mask:0x3
	v_mov_b32_dpp v115, v119 row_ror:8 row_mask:0xf bank_mask:0x3
	v_mov_b32_dpp v116, v244 row_ror:8 row_mask:0xf bank_mask:0xc
	v_mov_b32_dpp v117, v245 row_ror:8 row_mask:0xf bank_mask:0xc
	v_mov_b32_dpp v118, v246 row_ror:8 row_mask:0xf bank_mask:0xc
	v_mov_b32_dpp v119, v247 row_ror:8 row_mask:0xf bank_mask:0xc
	global_store_dwordx4 v187, v[116:119], s[16:17] offset:512
	global_store_dwordx4 v230, v[112:115], s[16:17] offset:512
	v_mov_b32_e32 v244, v158
	v_mov_b32_e32 v245, v159
	v_mov_b32_e32 v246, v160
	v_mov_b32_e32 v247, v161
	v_mov_b32_dpp v158, v162 row_ror:8 row_mask:0xf bank_mask:0xc
	v_mov_b32_dpp v159, v163 row_ror:8 row_mask:0xf bank_mask:0xc
	v_mov_b32_dpp v160, v164 row_ror:8 row_mask:0xf bank_mask:0xc
	v_mov_b32_dpp v161, v165 row_ror:8 row_mask:0xf bank_mask:0xc
	v_mov_b32_dpp v162, v244 row_ror:8 row_mask:0xf bank_mask:0x3
	v_mov_b32_dpp v163, v245 row_ror:8 row_mask:0xf bank_mask:0x3
	v_mov_b32_dpp v164, v246 row_ror:8 row_mask:0xf bank_mask:0x3
	v_mov_b32_dpp v165, v247 row_ror:8 row_mask:0xf bank_mask:0x3
	v_pk_add_f32 v[108:109], v[108:109], v[158:159]
	v_pk_add_f32 v[110:111], v[110:111], v[160:161]
	v_pk_add_f32 v[104:105], v[104:105], v[162:163]
	v_pk_add_f32 v[106:107], v[106:107], v[164:165]
	v_mov_b32_e32 v244, v104
	v_mov_b32_e32 v245, v105
	v_mov_b32_e32 v246, v106
	v_mov_b32_e32 v247, v107
; #define EPI_FOR(u) \
;     _Pragma("unroll") for (int ai = 0; ai < 2; ++ai) _Pragma("unroll") for (int m = 0; m < 4; ++m) _Pragma("unroll") for (int bj = 0; bj < 2; ++bj)
; #define EPI_COL(u) (EPI_CB(u) + 8 * fq)
;     DI void operator()(const Acc& acc, const Unit& u, int wr, int wc, int fr, int fq) const {
;         EPI_FOR(u) {
;             const int row = EPI_ROW(u), col = EPI_COL(u);
;             const float* rp = res + (size_t)row * 1024 + col; float* op = out + (size_t)row * 1024 + col;
;             const f32x4 r0 = *(const f32x4*)rp, r1 = *(const f32x4*)(rp + 4);
;             *(f32x4*)op = r0 + acc[ai][bj][m][0]; *(f32x4*)(op + 4) = r1 + acc[ai][bj][m][1];
;         }
	v_mov_b32_dpp v104, v108 row_ror:8 row_mask:0xf bank_mask:0x3
	v_mov_b32_dpp v105, v109 row_ror:8 row_mask:0xf bank_mask:0x3
	v_mov_b32_dpp v106, v110 row_ror:8 row_mask:0xf bank_mask:0x3
	v_mov_b32_dpp v107, v111 row_ror:8 row_mask:0xf bank_mask:0x3
	v_mov_b32_dpp v108, v244 row_ror:8 row_mask:0xf bank_mask:0xc
	v_mov_b32_dpp v109, v245 row_ror:8 row_mask:0xf bank_mask:0xc
	v_mov_b32_dpp v110, v246 row_ror:8 row_mask:0xf bank_mask:0xc
	v_mov_b32_dpp v111, v247 row_ror:8 row_mask:0xf bank_mask:0xc
	v_add_u32_e32 v187, 0x10000, v186
	v_add_u32_e32 v230, 0x18000, v186
	global_store_dwordx4 v187, v[108:111], s[16:17]
	global_store_dwordx4 v230, v[104:107], s[16:17]
	v_mov_b32_e32 v244, v166
	v_mov_b32_e32 v245, v167
	v_mov_b32_e32 v246, v168
	v_mov_b32_e32 v247, v169
	v_mov_b32_dpp v166, v170 row_ror:8 row_mask:0xf bank_mask:0xc
	v_mov_b32_dpp v167, v171 row_ror:8 row_mask:0xf bank_mask:0xc
	v_mov_b32_dpp v168, v172 row_ror:8 row_mask:0xf bank_mask:0xc
	v_mov_b32_dpp v169, v173 row_ror:8 row_mask:0xf bank_mask:0xc
	v_mov_b32_dpp v170, v244 row_ror:8 row_mask:0xf bank_mask:0x3
	v_mov_b32_dpp v171, v245 row_ror:8 row_mask:0xf bank_mask:0x3
	v_mov_b32_dpp v172, v246 row_ror:8 row_mask:0xf bank_mask:0x3
	v_mov_b32_dpp v173, v247 row_ror:8 row_mask:0xf bank_mask:0x3
	v_pk_add_f32 v[100:101], v[100:101], v[166:167]
	v_pk_add_f32 v[102:103], v[102:103], v[168:169]
	v_pk_add_f32 v[96:97], v[96:97], v[170:171]
	v_pk_add_f32 v[98:99], v[98:99], v[172:173]
	v_mov_b32_e32 v244, v96
	v_mov_b32_e32 v245, v97
	v_mov_b32_e32 v246, v98
	v_mov_b32_e32 v247, v99
	v_mov_b32_dpp v96, v100 row_ror:8 row_mask:0xf bank_mask:0x3
	v_mov_b32_dpp v97, v101 row_ror:8 row_mask:0xf bank_mask:0x3
	v_mov_b32_dpp v98, v102 row_ror:8 row_mask:0xf bank_mask:0x3
	v_mov_b32_dpp v99, v103 row_ror:8 row_mask:0xf bank_mask:0x3
	v_mov_b32_dpp v100, v244 row_ror:8 row_mask:0xf bank_mask:0xc
	v_mov_b32_dpp v101, v245 row_ror:8 row_mask:0xf bank_mask:0xc
	v_mov_b32_dpp v102, v246 row_ror:8 row_mask:0xf bank_mask:0xc
	v_mov_b32_dpp v103, v247 row_ror:8 row_mask:0xf bank_mask:0xc
	global_store_dwordx4 v187, v[100:103], s[16:17] offset:512
	global_store_dwordx4 v230, v[96:99], s[16:17] offset:512
	v_add_u32_e32 v187, 0x80000, v186
	v_add_u32_e32 v230, 0x88000, v186
	global_load_dwordx4 v[138:141], v187, s[16:17]
	global_load_dwordx4 v[146:149], v230, s[16:17]
	global_load_dwordx4 v[150:153], v187, s[16:17] offset:512
	global_load_dwordx4 v[154:157], v230, s[16:17] offset:512
	v_add_u32_e32 v187, 0x90000, v186
	v_add_u32_e32 v230, 0x98000, v186
	global_load_dwordx4 v[158:161], v187, s[16:17]
	global_load_dwordx4 v[162:165], v230, s[16:17]
	global_load_dwordx4 v[166:169], v187, s[16:17] offset:512
	global_load_dwordx4 v[170:173], v230, s[16:17] offset:512
	s_waitcnt vmcnt(16)
	v_mov_b32_e32 v244, v174
	v_mov_b32_e32 v245, v175
	v_mov_b32_e32 v246, v176
	v_mov_b32_e32 v247, v177
	v_mov_b32_dpp v174, v178 row_ror:8 row_mask:0xf bank_mask:0xc
	v_mov_b32_dpp v175, v179 row_ror:8 row_mask:0xf bank_mask:0xc
	v_mov_b32_dpp v176, v180 row_ror:8 row_mask:0xf bank_mask:0xc
	v_mov_b32_dpp v177, v181 row_ror:8 row_mask:0xf bank_mask:0xc
	v_mov_b32_dpp v178, v244 row_ror:8 row_mask:0xf bank_mask:0x3
	v_mov_b32_dpp v179, v245 row_ror:8 row_mask:0xf bank_mask:0x3
	v_mov_b32_dpp v180, v246 row_ror:8 row_mask:0xf bank_mask:0x3
	v_mov_b32_dpp v181, v247 row_ror:8 row_mask:0xf bank_mask:0x3
	v_pk_add_f32 v[92:93], v[92:93], v[174:175]
	v_pk_add_f32 v[94:95], v[94:95], v[176:177]
	v_pk_add_f32 v[88:89], v[88:89], v[178:179]
	v_pk_add_f32 v[90:91], v[90:91], v[180:181]
	v_mov_b32_e32 v244, v88
	v_mov_b32_e32 v245, v89
	v_mov_b32_e32 v246, v90
	v_mov_b32_e32 v247, v91
	v_mov_b32_dpp v88, v92 row_ror:8 row_mask:0xf bank_mask:0x3
	v_mov_b32_dpp v89, v93 row_ror:8 row_mask:0xf bank_mask:0x3
	v_mov_b32_dpp v90, v94 row_ror:8 row_mask:0xf bank_mask:0x3
	v_mov_b32_dpp v91, v95 row_ror:8 row_mask:0xf bank_mask:0x3
	v_mov_b32_dpp v92, v244 row_ror:8 row_mask:0xf bank_mask:0xc
	v_mov_b32_dpp v93, v245 row_ror:8 row_mask:0xf bank_mask:0xc
	v_mov_b32_dpp v94, v246 row_ror:8 row_mask:0xf bank_mask:0xc
	v_mov_b32_dpp v95, v247 row_ror:8 row_mask:0xf bank_mask:0xc
	v_add_u32_e32 v187, 0x20000, v186
	v_add_u32_e32 v230, 0x28000, v186
	global_store_dwordx4 v187, v[92:95], s[16:17]
	global_store_dwordx4 v230, v[88:91], s[16:17]
	v_mov_b32_e32 v244, v182
	v_mov_b32_e32 v245, v183
	v_mov_b32_e32 v246, v184
	v_mov_b32_e32 v247, v185
	v_mov_b32_dpp v182, v210 row_ror:8 row_mask:0xf bank_mask:0xc
	v_mov_b32_dpp v183, v211 row_ror:8 row_mask:0xf bank_mask:0xc
	v_mov_b32_dpp v184, v212 row_ror:8 row_mask:0xf bank_mask:0xc
	v_mov_b32_dpp v185, v213 row_ror:8 row_mask:0xf bank_mask:0xc
	v_mov_b32_dpp v210, v244 row_ror:8 row_mask:0xf bank_mask:0x3
	v_mov_b32_dpp v211, v245 row_ror:8 row_mask:0xf bank_mask:0x3
	v_mov_b32_dpp v212, v246 row_ror:8 row_mask:0xf bank_mask:0x3
	v_mov_b32_dpp v213, v247 row_ror:8 row_mask:0xf bank_mask:0x3
	v_pk_add_f32 v[84:85], v[84:85], v[182:183]
	v_pk_add_f32 v[86:87], v[86:87], v[184:185]
	v_pk_add_f32 v[80:81], v[80:81], v[210:211]
	v_pk_add_f32 v[82:83], v[82:83], v[212:213]
	v_mov_b32_e32 v244, v80
	v_mov_b32_e32 v245, v81
	v_mov_b32_e32 v246, v82
	v_mov_b32_e32 v247, v83
	v_mov_b32_dpp v80, v84 row_ror:8 row_mask:0xf bank_mask:0x3
	v_mov_b32_dpp v81, v85 row_ror:8 row_mask:0xf bank_mask:0x3
	v_mov_b32_dpp v82, v86 row_ror:8 row_mask:0xf bank_mask:0x3
	v_mov_b32_dpp v83, v87 row_ror:8 row_mask:0xf bank_mask:0x3
	v_mov_b32_dpp v84, v244 row_ror:8 row_mask:0xf bank_mask:0xc
	v_mov_b32_dpp v85, v245 row_ror:8 row_mask:0xf bank_mask:0xc
	v_mov_b32_dpp v86, v246 row_ror:8 row_mask:0xf bank_mask:0xc
; #define EPI_FOR(u) \
;     _Pragma("unroll") for (int ai = 0; ai < 2; ++ai) _Pragma("unroll") for (int m = 0; m < 4; ++m) _Pragma("unroll") for (int bj = 0; bj < 2; ++bj)
; #define EPI_COL(u) (EPI_CB(u) + 8 * fq)
;     DI void operator()(const Acc& acc, const Unit& u, int wr, int wc, int fr, int fq) const {
;         EPI_FOR(u) {
;             const int row = EPI_ROW(u), col = EPI_COL(u);
;             const float* rp = res + (size_t)row * 1024 + col; float* op = out + (size_t)row * 1024 + col;
;             const f32x4 r0 = *(const f32x4*)rp, r1 = *(const f32x4*)(rp + 4);
;             *(f32x4*)op = r0 + acc[ai][bj][m][0]; *(f32x4*)(op + 4) = r1 + acc[ai][bj][m][1];
;         }
	v_mov_b32_dpp v87, v247 row_ror:8 row_mask:0xf bank_mask:0xc
	global_store_dwordx4 v187, v[84:87], s[16:17] offset:512
	global_store_dwordx4 v230, v[80:83], s[16:17] offset:512
	v_mov_b32_e32 v244, v214
	v_mov_b32_e32 v245, v215
	v_mov_b32_e32 v246, v216
	v_mov_b32_e32 v247, v217
	v_mov_b32_dpp v214, v218 row_ror:8 row_mask:0xf bank_mask:0xc
	v_mov_b32_dpp v215, v219 row_ror:8 row_mask:0xf bank_mask:0xc
	v_mov_b32_dpp v216, v220 row_ror:8 row_mask:0xf bank_mask:0xc
	v_mov_b32_dpp v217, v221 row_ror:8 row_mask:0xf bank_mask:0xc
	v_mov_b32_dpp v218, v244 row_ror:8 row_mask:0xf bank_mask:0x3
	v_mov_b32_dpp v219, v245 row_ror:8 row_mask:0xf bank_mask:0x3
	v_mov_b32_dpp v220, v246 row_ror:8 row_mask:0xf bank_mask:0x3
	v_mov_b32_dpp v221, v247 row_ror:8 row_mask:0xf bank_mask:0x3
	v_pk_add_f32 v[76:77], v[76:77], v[214:215]
	v_pk_add_f32 v[78:79], v[78:79], v[216:217]
	v_pk_add_f32 v[72:73], v[72:73], v[218:219]
	v_pk_add_f32 v[74:75], v[74:75], v[220:221]
	v_mov_b32_e32 v244, v72
	v_mov_b32_e32 v245, v73
	v_mov_b32_e32 v246, v74
	v_mov_b32_e32 v247, v75
	v_mov_b32_dpp v72, v76 row_ror:8 row_mask:0xf bank_mask:0x3
	v_mov_b32_dpp v73, v77 row_ror:8 row_mask:0xf bank_mask:0x3
	v_mov_b32_dpp v74, v78 row_ror:8 row_mask:0xf bank_mask:0x3
	v_mov_b32_dpp v75, v79 row_ror:8 row_mask:0xf bank_mask:0x3
	v_mov_b32_dpp v76, v244 row_ror:8 row_mask:0xf bank_mask:0xc
	v_mov_b32_dpp v77, v245 row_ror:8 row_mask:0xf bank_mask:0xc
	v_mov_b32_dpp v78, v246 row_ror:8 row_mask:0xf bank_mask:0xc
	v_mov_b32_dpp v79, v247 row_ror:8 row_mask:0xf bank_mask:0xc
	v_add_u32_e32 v187, 0x30000, v186
	v_add_u32_e32 v230, 0x38000, v186
	global_store_dwordx4 v187, v[76:79], s[16:17]
	global_store_dwordx4 v230, v[72:75], s[16:17]
	v_mov_b32_e32 v244, v222
	v_mov_b32_e32 v245, v223
	v_mov_b32_e32 v246, v224
	v_mov_b32_e32 v247, v225
	v_mov_b32_dpp v222, v226 row_ror:8 row_mask:0xf bank_mask:0xc
	v_mov_b32_dpp v223, v227 row_ror:8 row_mask:0xf bank_mask:0xc
	v_mov_b32_dpp v224, v228 row_ror:8 row_mask:0xf bank_mask:0xc
	v_mov_b32_dpp v225, v229 row_ror:8 row_mask:0xf bank_mask:0xc
	v_mov_b32_dpp v226, v244 row_ror:8 row_mask:0xf bank_mask:0x3
	v_mov_b32_dpp v227, v245 row_ror:8 row_mask:0xf bank_mask:0x3
	v_mov_b32_dpp v228, v246 row_ror:8 row_mask:0xf bank_mask:0x3
	v_mov_b32_dpp v229, v247 row_ror:8 row_mask:0xf bank_mask:0x3
	v_pk_add_f32 v[68:69], v[68:69], v[222:223]
	v_pk_add_f32 v[70:71], v[70:71], v[224:225]
	v_pk_add_f32 v[64:65], v[64:65], v[226:227]
	v_pk_add_f32 v[66:67], v[66:67], v[228:229]
	v_mov_b32_e32 v244, v64
	v_mov_b32_e32 v245, v65
	v_mov_b32_e32 v246, v66
	v_mov_b32_e32 v247, v67
	v_mov_b32_dpp v64, v68 row_ror:8 row_mask:0xf bank_mask:0x3
	v_mov_b32_dpp v65, v69 row_ror:8 row_mask:0xf bank_mask:0x3
	v_mov_b32_dpp v66, v70 row_ror:8 row_mask:0xf bank_mask:0x3
	v_mov_b32_dpp v67, v71 row_ror:8 row_mask:0xf bank_mask:0x3
	v_mov_b32_dpp v68, v244 row_ror:8 row_mask:0xf bank_mask:0xc
	v_mov_b32_dpp v69, v245 row_ror:8 row_mask:0xf bank_mask:0xc
	v_mov_b32_dpp v70, v246 row_ror:8 row_mask:0xf bank_mask:0xc
	v_mov_b32_dpp v71, v247 row_ror:8 row_mask:0xf bank_mask:0xc
	global_store_dwordx4 v187, v[68:71], s[16:17] offset:512
	global_store_dwordx4 v230, v[64:67], s[16:17] offset:512
	v_add_u32_e32 v187, 0xa0000, v186
	v_add_u32_e32 v230, 0xa8000, v186
	global_load_dwordx4 v[174:177], v187, s[16:17]
	global_load_dwordx4 v[178:181], v230, s[16:17]
	global_load_dwordx4 v[182:185], v187, s[16:17] offset:512
	global_load_dwordx4 v[210:213], v230, s[16:17] offset:512
	v_add_u32_e32 v187, 0xb0000, v186
	v_add_u32_e32 v230, 0xb8000, v186
	global_load_dwordx4 v[214:217], v187, s[16:17]
	global_load_dwordx4 v[218:221], v230, s[16:17]
	global_load_dwordx4 v[222:225], v187, s[16:17] offset:512
	global_load_dwordx4 v[226:229], v230, s[16:17] offset:512
	s_waitcnt vmcnt(16)
	v_mov_b32_e32 v244, v138
	v_mov_b32_e32 v245, v139
	v_mov_b32_e32 v246, v140
	v_mov_b32_e32 v247, v141
	v_mov_b32_dpp v138, v146 row_ror:8 row_mask:0xf bank_mask:0xc
	v_mov_b32_dpp v139, v147 row_ror:8 row_mask:0xf bank_mask:0xc
	v_mov_b32_dpp v140, v148 row_ror:8 row_mask:0xf bank_mask:0xc
	v_mov_b32_dpp v141, v149 row_ror:8 row_mask:0xf bank_mask:0xc
	v_mov_b32_dpp v146, v244 row_ror:8 row_mask:0xf bank_mask:0x3
	v_mov_b32_dpp v147, v245 row_ror:8 row_mask:0xf bank_mask:0x3
	v_mov_b32_dpp v148, v246 row_ror:8 row_mask:0xf bank_mask:0x3
	v_mov_b32_dpp v149, v247 row_ror:8 row_mask:0xf bank_mask:0x3
	v_pk_add_f32 v[60:61], v[60:61], v[138:139]
	v_pk_add_f32 v[62:63], v[62:63], v[140:141]
	v_pk_add_f32 v[56:57], v[56:57], v[146:147]
	v_pk_add_f32 v[58:59], v[58:59], v[148:149]
	v_mov_b32_e32 v244, v56
	v_mov_b32_e32 v245, v57
	v_mov_b32_e32 v246, v58
	v_mov_b32_e32 v247, v59
	v_mov_b32_dpp v56, v60 row_ror:8 row_mask:0xf bank_mask:0x3
	v_mov_b32_dpp v57, v61 row_ror:8 row_mask:0xf bank_mask:0x3
	v_mov_b32_dpp v58, v62 row_ror:8 row_mask:0xf bank_mask:0x3
	v_mov_b32_dpp v59, v63 row_ror:8 row_mask:0xf bank_mask:0x3
	v_mov_b32_dpp v60, v244 row_ror:8 row_mask:0xf bank_mask:0xc
	v_mov_b32_dpp v61, v245 row_ror:8 row_mask:0xf bank_mask:0xc
	v_mov_b32_dpp v62, v246 row_ror:8 row_mask:0xf bank_mask:0xc
	v_mov_b32_dpp v63, v247 row_ror:8 row_mask:0xf bank_mask:0xc
	v_add_u32_e32 v187, 0x80000, v186
	v_add_u32_e32 v230, 0x88000, v186
	global_store_dwordx4 v187, v[60:63], s[16:17]
	global_store_dwordx4 v230, v[56:59], s[16:17]
	v_mov_b32_e32 v244, v150
	v_mov_b32_e32 v245, v151
	v_mov_b32_e32 v246, v152
	v_mov_b32_e32 v247, v153
	v_mov_b32_dpp v150, v154 row_ror:8 row_mask:0xf bank_mask:0xc
	v_mov_b32_dpp v151, v155 row_ror:8 row_mask:0xf bank_mask:0xc
	v_mov_b32_dpp v152, v156 row_ror:8 row_mask:0xf bank_mask:0xc
; #define EPI_FOR(u) \
;     _Pragma("unroll") for (int ai = 0; ai < 2; ++ai) _Pragma("unroll") for (int m = 0; m < 4; ++m) _Pragma("unroll") for (int bj = 0; bj < 2; ++bj)
; #define EPI_COL(u) (EPI_CB(u) + 8 * fq)
;     DI void operator()(const Acc& acc, const Unit& u, int wr, int wc, int fr, int fq) const {
;         EPI_FOR(u) {
;             const int row = EPI_ROW(u), col = EPI_COL(u);
;             const float* rp = res + (size_t)row * 1024 + col; float* op = out + (size_t)row * 1024 + col;
;             const f32x4 r0 = *(const f32x4*)rp, r1 = *(const f32x4*)(rp + 4);
;             *(f32x4*)op = r0 + acc[ai][bj][m][0]; *(f32x4*)(op + 4) = r1 + acc[ai][bj][m][1];
;         }
	v_mov_b32_dpp v153, v157 row_ror:8 row_mask:0xf bank_mask:0xc
	v_mov_b32_dpp v154, v244 row_ror:8 row_mask:0xf bank_mask:0x3
	v_mov_b32_dpp v155, v245 row_ror:8 row_mask:0xf bank_mask:0x3
	v_mov_b32_dpp v156, v246 row_ror:8 row_mask:0xf bank_mask:0x3
	v_mov_b32_dpp v157, v247 row_ror:8 row_mask:0xf bank_mask:0x3
	v_pk_add_f32 v[52:53], v[52:53], v[150:151]
	v_pk_add_f32 v[54:55], v[54:55], v[152:153]
	v_pk_add_f32 v[48:49], v[48:49], v[154:155]
	v_pk_add_f32 v[50:51], v[50:51], v[156:157]
	v_mov_b32_e32 v244, v48
	v_mov_b32_e32 v245, v49
	v_mov_b32_e32 v246, v50
	v_mov_b32_e32 v247, v51
	v_mov_b32_dpp v48, v52 row_ror:8 row_mask:0xf bank_mask:0x3
	v_mov_b32_dpp v49, v53 row_ror:8 row_mask:0xf bank_mask:0x3
	v_mov_b32_dpp v50, v54 row_ror:8 row_mask:0xf bank_mask:0x3
	v_mov_b32_dpp v51, v55 row_ror:8 row_mask:0xf bank_mask:0x3
	v_mov_b32_dpp v52, v244 row_ror:8 row_mask:0xf bank_mask:0xc
	v_mov_b32_dpp v53, v245 row_ror:8 row_mask:0xf bank_mask:0xc
	v_mov_b32_dpp v54, v246 row_ror:8 row_mask:0xf bank_mask:0xc
	v_mov_b32_dpp v55, v247 row_ror:8 row_mask:0xf bank_mask:0xc
	global_store_dwordx4 v187, v[52:55], s[16:17] offset:512
	global_store_dwordx4 v230, v[48:51], s[16:17] offset:512
	v_mov_b32_e32 v244, v158
	v_mov_b32_e32 v245, v159
	v_mov_b32_e32 v246, v160
	v_mov_b32_e32 v247, v161
	v_mov_b32_dpp v158, v162 row_ror:8 row_mask:0xf bank_mask:0xc
	v_mov_b32_dpp v159, v163 row_ror:8 row_mask:0xf bank_mask:0xc
	v_mov_b32_dpp v160, v164 row_ror:8 row_mask:0xf bank_mask:0xc
	v_mov_b32_dpp v161, v165 row_ror:8 row_mask:0xf bank_mask:0xc
	v_mov_b32_dpp v162, v244 row_ror:8 row_mask:0xf bank_mask:0x3
	v_mov_b32_dpp v163, v245 row_ror:8 row_mask:0xf bank_mask:0x3
	v_mov_b32_dpp v164, v246 row_ror:8 row_mask:0xf bank_mask:0x3
	v_mov_b32_dpp v165, v247 row_ror:8 row_mask:0xf bank_mask:0x3
	v_pk_add_f32 v[44:45], v[44:45], v[158:159]
	v_pk_add_f32 v[46:47], v[46:47], v[160:161]
	v_pk_add_f32 v[40:41], v[40:41], v[162:163]
	v_pk_add_f32 v[42:43], v[42:43], v[164:165]
	v_mov_b32_e32 v244, v40
	v_mov_b32_e32 v245, v41
	v_mov_b32_e32 v246, v42
	v_mov_b32_e32 v247, v43
	v_mov_b32_dpp v40, v44 row_ror:8 row_mask:0xf bank_mask:0x3
	v_mov_b32_dpp v41, v45 row_ror:8 row_mask:0xf bank_mask:0x3
	v_mov_b32_dpp v42, v46 row_ror:8 row_mask:0xf bank_mask:0x3
	v_mov_b32_dpp v43, v47 row_ror:8 row_mask:0xf bank_mask:0x3
	v_mov_b32_dpp v44, v244 row_ror:8 row_mask:0xf bank_mask:0xc
	v_mov_b32_dpp v45, v245 row_ror:8 row_mask:0xf bank_mask:0xc
	v_mov_b32_dpp v46, v246 row_ror:8 row_mask:0xf bank_mask:0xc
	v_mov_b32_dpp v47, v247 row_ror:8 row_mask:0xf bank_mask:0xc
	v_add_u32_e32 v187, 0x90000, v186
	v_add_u32_e32 v230, 0x98000, v186
	global_store_dwordx4 v187, v[44:47], s[16:17]
	global_store_dwordx4 v230, v[40:43], s[16:17]
	v_mov_b32_e32 v244, v166
	v_mov_b32_e32 v245, v167
	v_mov_b32_e32 v246, v168
	v_mov_b32_e32 v247, v169
	v_mov_b32_dpp v166, v170 row_ror:8 row_mask:0xf bank_mask:0xc
	v_mov_b32_dpp v167, v171 row_ror:8 row_mask:0xf bank_mask:0xc
	v_mov_b32_dpp v168, v172 row_ror:8 row_mask:0xf bank_mask:0xc
	v_mov_b32_dpp v169, v173 row_ror:8 row_mask:0xf bank_mask:0xc
	v_mov_b32_dpp v170, v244 row_ror:8 row_mask:0xf bank_mask:0x3
	v_mov_b32_dpp v171, v245 row_ror:8 row_mask:0xf bank_mask:0x3
	v_mov_b32_dpp v172, v246 row_ror:8 row_mask:0xf bank_mask:0x3
	v_mov_b32_dpp v173, v247 row_ror:8 row_mask:0xf bank_mask:0x3
	v_pk_add_f32 v[36:37], v[36:37], v[166:167]
	v_pk_add_f32 v[38:39], v[38:39], v[168:169]
	v_pk_add_f32 v[32:33], v[32:33], v[170:171]
	v_pk_add_f32 v[34:35], v[34:35], v[172:173]
	v_mov_b32_e32 v244, v32
	v_mov_b32_e32 v245, v33
	v_mov_b32_e32 v246, v34
	v_mov_b32_e32 v247, v35
	v_mov_b32_dpp v32, v36 row_ror:8 row_mask:0xf bank_mask:0x3
	v_mov_b32_dpp v33, v37 row_ror:8 row_mask:0xf bank_mask:0x3
	v_mov_b32_dpp v34, v38 row_ror:8 row_mask:0xf bank_mask:0x3
	v_mov_b32_dpp v35, v39 row_ror:8 row_mask:0xf bank_mask:0x3
	v_mov_b32_dpp v36, v244 row_ror:8 row_mask:0xf bank_mask:0xc
	v_mov_b32_dpp v37, v245 row_ror:8 row_mask:0xf bank_mask:0xc
	v_mov_b32_dpp v38, v246 row_ror:8 row_mask:0xf bank_mask:0xc
	v_mov_b32_dpp v39, v247 row_ror:8 row_mask:0xf bank_mask:0xc
	global_store_dwordx4 v187, v[36:39], s[16:17] offset:512
	global_store_dwordx4 v230, v[32:35], s[16:17] offset:512
	s_waitcnt vmcnt(8)
; #define PG8_BAR __builtin_amdgcn_s_barrier()
; #define EPI_FOR(u) \
;     _Pragma("unroll") for (int ai = 0; ai < 2; ++ai) _Pragma("unroll") for (int m = 0; m < 4; ++m) _Pragma("unroll") for (int bj = 0; bj < 2; ++bj)
; #define EPI_COL(u) (EPI_CB(u) + 8 * fq)
; template <class Epi>
; DI void gemm_phase(LAS unsigned char* lds, const Gemm g, const Sched& S, const Epi& E) {
;     ...
;         if (!has_next) break;
; #pragma unroll
;         for (int a = 0; a < 2; ++a)
; #pragma unroll
;             for (int b = 0; b < 2; ++b)
; #pragma unroll
;                 for (int m = 0; m < 4; ++m)
; #pragma unroll
;                     for (int n = 0; n < 2; ++n) acc[a][b][m][n] = (f32x4){0.f, 0.f, 0.f, 0.f};
;         cur = nxt; cA = nA; cB = nB; ++ui;
;         if (wr == 1) PG8_BAR;
;     DI void operator()(const Acc& acc, const Unit& u, int wr, int wc, int fr, int fq) const {
;         EPI_FOR(u) {
;             const int row = EPI_ROW(u), col = EPI_COL(u);
;             const float* rp = res + (size_t)row * 1024 + col; float* op = out + (size_t)row * 1024 + col;
;             const f32x4 r0 = *(const f32x4*)rp, r1 = *(const f32x4*)(rp + 4);
;             *(f32x4*)op = r0 + acc[ai][bj][m][0]; *(f32x4*)(op + 4) = r1 + acc[ai][bj][m][1];
;         }
	v_mov_b32_e32 v244, v174
	v_mov_b32_e32 v245, v175
	v_mov_b32_e32 v246, v176
	v_mov_b32_e32 v247, v177
	v_mov_b32_dpp v174, v178 row_ror:8 row_mask:0xf bank_mask:0xc
	v_mov_b32_dpp v175, v179 row_ror:8 row_mask:0xf bank_mask:0xc
	v_mov_b32_dpp v176, v180 row_ror:8 row_mask:0xf bank_mask:0xc
	v_mov_b32_dpp v177, v181 row_ror:8 row_mask:0xf bank_mask:0xc
	v_mov_b32_dpp v178, v244 row_ror:8 row_mask:0xf bank_mask:0x3
	v_mov_b32_dpp v179, v245 row_ror:8 row_mask:0xf bank_mask:0x3
	v_mov_b32_dpp v180, v246 row_ror:8 row_mask:0xf bank_mask:0x3
	v_mov_b32_dpp v181, v247 row_ror:8 row_mask:0xf bank_mask:0x3
	v_pk_add_f32 v[28:29], v[28:29], v[174:175]
	v_pk_add_f32 v[30:31], v[30:31], v[176:177]
	v_pk_add_f32 v[24:25], v[24:25], v[178:179]
	v_pk_add_f32 v[26:27], v[26:27], v[180:181]
	v_mov_b32_e32 v244, v24
	v_mov_b32_e32 v245, v25
	v_mov_b32_e32 v246, v26
	v_mov_b32_e32 v247, v27
	v_mov_b32_dpp v24, v28 row_ror:8 row_mask:0xf bank_mask:0x3
	v_mov_b32_dpp v25, v29 row_ror:8 row_mask:0xf bank_mask:0x3
	v_mov_b32_dpp v26, v30 row_ror:8 row_mask:0xf bank_mask:0x3
	v_mov_b32_dpp v27, v31 row_ror:8 row_mask:0xf bank_mask:0x3
	v_mov_b32_dpp v28, v244 row_ror:8 row_mask:0xf bank_mask:0xc
	v_mov_b32_dpp v29, v245 row_ror:8 row_mask:0xf bank_mask:0xc
	v_mov_b32_dpp v30, v246 row_ror:8 row_mask:0xf bank_mask:0xc
	v_mov_b32_dpp v31, v247 row_ror:8 row_mask:0xf bank_mask:0xc
	v_add_u32_e32 v187, 0xa0000, v186
	v_add_u32_e32 v230, 0xa8000, v186
	global_store_dwordx4 v187, v[28:31], s[16:17]
	global_store_dwordx4 v230, v[24:27], s[16:17]
	v_mov_b32_e32 v244, v182
	v_mov_b32_e32 v245, v183
	v_mov_b32_e32 v246, v184
	v_mov_b32_e32 v247, v185
	v_mov_b32_dpp v182, v210 row_ror:8 row_mask:0xf bank_mask:0xc
	v_mov_b32_dpp v183, v211 row_ror:8 row_mask:0xf bank_mask:0xc
	v_mov_b32_dpp v184, v212 row_ror:8 row_mask:0xf bank_mask:0xc
	v_mov_b32_dpp v185, v213 row_ror:8 row_mask:0xf bank_mask:0xc
	v_mov_b32_dpp v210, v244 row_ror:8 row_mask:0xf bank_mask:0x3
	v_mov_b32_dpp v211, v245 row_ror:8 row_mask:0xf bank_mask:0x3
	v_mov_b32_dpp v212, v246 row_ror:8 row_mask:0xf bank_mask:0x3
	v_mov_b32_dpp v213, v247 row_ror:8 row_mask:0xf bank_mask:0x3
	v_pk_add_f32 v[20:21], v[20:21], v[182:183]
	v_pk_add_f32 v[22:23], v[22:23], v[184:185]
	v_pk_add_f32 v[16:17], v[16:17], v[210:211]
	v_pk_add_f32 v[18:19], v[18:19], v[212:213]
	v_mov_b32_e32 v244, v16
	v_mov_b32_e32 v245, v17
	v_mov_b32_e32 v246, v18
	v_mov_b32_e32 v247, v19
	v_mov_b32_dpp v16, v20 row_ror:8 row_mask:0xf bank_mask:0x3
	v_mov_b32_dpp v17, v21 row_ror:8 row_mask:0xf bank_mask:0x3
	v_mov_b32_dpp v18, v22 row_ror:8 row_mask:0xf bank_mask:0x3
	v_mov_b32_dpp v19, v23 row_ror:8 row_mask:0xf bank_mask:0x3
	v_mov_b32_dpp v20, v244 row_ror:8 row_mask:0xf bank_mask:0xc
	v_mov_b32_dpp v21, v245 row_ror:8 row_mask:0xf bank_mask:0xc
	v_mov_b32_dpp v22, v246 row_ror:8 row_mask:0xf bank_mask:0xc
	v_mov_b32_dpp v23, v247 row_ror:8 row_mask:0xf bank_mask:0xc
	global_store_dwordx4 v187, v[20:23], s[16:17] offset:512
	global_store_dwordx4 v230, v[16:19], s[16:17] offset:512
	v_mov_b32_e32 v244, v214
	v_mov_b32_e32 v245, v215
	v_mov_b32_e32 v246, v216
	v_mov_b32_e32 v247, v217
	v_mov_b32_dpp v214, v218 row_ror:8 row_mask:0xf bank_mask:0xc
	v_mov_b32_dpp v215, v219 row_ror:8 row_mask:0xf bank_mask:0xc
	v_mov_b32_dpp v216, v220 row_ror:8 row_mask:0xf bank_mask:0xc
	v_mov_b32_dpp v217, v221 row_ror:8 row_mask:0xf bank_mask:0xc
	v_mov_b32_dpp v218, v244 row_ror:8 row_mask:0xf bank_mask:0x3
	v_mov_b32_dpp v219, v245 row_ror:8 row_mask:0xf bank_mask:0x3
	v_mov_b32_dpp v220, v246 row_ror:8 row_mask:0xf bank_mask:0x3
	v_mov_b32_dpp v221, v247 row_ror:8 row_mask:0xf bank_mask:0x3
	v_pk_add_f32 v[12:13], v[12:13], v[214:215]
	v_pk_add_f32 v[14:15], v[14:15], v[216:217]
	v_pk_add_f32 v[8:9], v[8:9], v[218:219]
	v_pk_add_f32 v[10:11], v[10:11], v[220:221]
	v_mov_b32_e32 v244, v8
	v_mov_b32_e32 v245, v9
	v_mov_b32_e32 v246, v10
	v_mov_b32_e32 v247, v11
	v_mov_b32_dpp v8, v12 row_ror:8 row_mask:0xf bank_mask:0x3
	v_mov_b32_dpp v9, v13 row_ror:8 row_mask:0xf bank_mask:0x3
	v_mov_b32_dpp v10, v14 row_ror:8 row_mask:0xf bank_mask:0x3
	v_mov_b32_dpp v11, v15 row_ror:8 row_mask:0xf bank_mask:0x3
	v_mov_b32_dpp v12, v244 row_ror:8 row_mask:0xf bank_mask:0xc
	v_mov_b32_dpp v13, v245 row_ror:8 row_mask:0xf bank_mask:0xc
	v_mov_b32_dpp v14, v246 row_ror:8 row_mask:0xf bank_mask:0xc
	v_mov_b32_dpp v15, v247 row_ror:8 row_mask:0xf bank_mask:0xc
	v_add_u32_e32 v187, 0xb0000, v186
	v_add_u32_e32 v230, 0xb8000, v186
	global_store_dwordx4 v187, v[12:15], s[16:17]
	global_store_dwordx4 v230, v[8:11], s[16:17]
	v_mov_b32_e32 v244, v222
	v_mov_b32_e32 v245, v223
	v_mov_b32_e32 v246, v224
	v_mov_b32_e32 v247, v225
	v_mov_b32_dpp v222, v226 row_ror:8 row_mask:0xf bank_mask:0xc
	v_mov_b32_dpp v223, v227 row_ror:8 row_mask:0xf bank_mask:0xc
	v_mov_b32_dpp v224, v228 row_ror:8 row_mask:0xf bank_mask:0xc
	v_mov_b32_dpp v225, v229 row_ror:8 row_mask:0xf bank_mask:0xc
	v_mov_b32_dpp v226, v244 row_ror:8 row_mask:0xf bank_mask:0x3
	v_mov_b32_dpp v227, v245 row_ror:8 row_mask:0xf bank_mask:0x3
	v_mov_b32_dpp v228, v246 row_ror:8 row_mask:0xf bank_mask:0x3
	v_mov_b32_dpp v229, v247 row_ror:8 row_mask:0xf bank_mask:0x3
	v_pk_add_f32 v[4:5], v[4:5], v[222:223]
	v_pk_add_f32 v[6:7], v[6:7], v[224:225]
	v_pk_add_f32 v[0:1], v[0:1], v[226:227]
	v_pk_add_f32 v[2:3], v[2:3], v[228:229]
	v_mov_b32_e32 v244, v0
	v_mov_b32_e32 v245, v1
	v_mov_b32_e32 v246, v2
	v_mov_b32_e32 v247, v3
	v_mov_b32_dpp v0, v4 row_ror:8 row_mask:0xf bank_mask:0x3
	v_mov_b32_dpp v1, v5 row_ror:8 row_mask:0xf bank_mask:0x3
	v_mov_b32_dpp v2, v6 row_ror:8 row_mask:0xf bank_mask:0x3
	v_mov_b32_dpp v3, v7 row_ror:8 row_mask:0xf bank_mask:0x3
	v_mov_b32_dpp v4, v244 row_ror:8 row_mask:0xf bank_mask:0xc
	v_mov_b32_dpp v5, v245 row_ror:8 row_mask:0xf bank_mask:0xc
	v_mov_b32_dpp v6, v246 row_ror:8 row_mask:0xf bank_mask:0xc
	v_mov_b32_dpp v7, v247 row_ror:8 row_mask:0xf bank_mask:0xc
	global_store_dwordx4 v187, v[4:7], s[16:17] offset:512
	global_store_dwordx4 v230, v[0:3], s[16:17] offset:512
	s_cbranch_vccnz .LBB0_1396
	s_andn2_b64 vcc, exec, s[12:13]
	s_cbranch_vccnz .LBB0_1395
	s_barrier
	s_branch .LBB0_1395
